# plus attention-phase bias table init: four table loads in flight and one kernarg load instead of four serial load-wait iterations
# speedup vs baseline: 1.0033x; 1.0033x over previous
; #define rel_table (karg(8))
; __global__ void __launch_bounds__(512, 2) fwd_mega(Args args) {
;     ...
;             for (int i = tid; i < 8 * 256; i += 512) { const int hh = i >> 8, j = i & 255; int rel = j - 63; rel = rel > 128 ? 128 : rel; T[hh * 256 + j] = rel_table[(size_t)l * 8 * 257 + hh * 257 + rel + 128] * LOG2E; }
.LBB0_511:
	s_mov_b64 s[6:7], s[88:89]
	s_load_dwordx2 s[6:7], s[6:7], 0x40
	s_waitcnt lgkmcnt(0)
	s_add_u32 s6, s6, s1
	s_addc_u32 s7, s7, s0
	v_lshrrev_b32_e32 v2, 8, v1
	v_mul_i32_i24_e32 v2, 0x101, v2
	v_ashrrev_i32_e32 v3, 31, v2
	v_lshl_add_u64 v[2:3], v[2:3], 2, s[6:7]
	v_lshl_add_u64 v[2:3], v[2:3], 0, v[188:189]
	global_load_dword v120, v[2:3], off offset:260
	v_add_u32_e32 v124, 0x200, v1
	v_lshrrev_b32_e32 v2, 8, v124
	v_mul_i32_i24_e32 v2, 0x101, v2
	v_ashrrev_i32_e32 v3, 31, v2
	v_lshl_add_u64 v[2:3], v[2:3], 2, s[6:7]
	v_lshl_add_u64 v[2:3], v[2:3], 0, v[188:189]
	global_load_dword v121, v[2:3], off offset:260
	v_add_u32_e32 v124, 0x400, v1
	v_lshrrev_b32_e32 v2, 8, v124
	v_mul_i32_i24_e32 v2, 0x101, v2
	v_ashrrev_i32_e32 v3, 31, v2
	v_lshl_add_u64 v[2:3], v[2:3], 2, s[6:7]
	v_lshl_add_u64 v[2:3], v[2:3], 0, v[188:189]
	global_load_dword v122, v[2:3], off offset:260
	v_add_u32_e32 v124, 0x600, v1
	v_lshrrev_b32_e32 v2, 8, v124
	v_mul_i32_i24_e32 v2, 0x101, v2
	v_ashrrev_i32_e32 v3, 31, v2
	v_lshl_add_u64 v[2:3], v[2:3], 2, s[6:7]
	v_lshl_add_u64 v[2:3], v[2:3], 0, v[188:189]
	global_load_dword v123, v[2:3], off offset:260
	s_waitcnt vmcnt(0)
	v_mul_f32_e32 v120, 0x3fb8aa3b, v120
	ds_write_b32 v0, v120
	v_mul_f32_e32 v121, 0x3fb8aa3b, v121
	ds_write_b32 v0, v121 offset:2048
	v_mul_f32_e32 v122, 0x3fb8aa3b, v122
	ds_write_b32 v0, v122 offset:4096
	v_mul_f32_e32 v123, 0x3fb8aa3b, v123
	ds_write_b32 v0, v123 offset:6144
